# k28_align
# speedup vs baseline: 1.0087x; 1.0087x over previous
; DI f32x16 fzero() { f32x16 z; for (int i = 0; i < 16; ++i) z[i] = 0.f; return z; }
; template <int NT, class Epi>
; DI void gemm_tile(const u16* __restrict__ A, int lda, const u16* __restrict__ Bt, int ldb, int K, int m0, int n0, const Epi& epi, char* smem) {
;   constexpr int BN = 64 * NT, NB8 = 2 * NT;
;   u16* As = (u16*)smem;
;   u16* Bs = As + 128 * 72;
;   const int tid = threadIdx.x, lane = tid & 63, wave = tid >> 6, r = lane & 31, h = lane >> 5;
;   const int wm = wave >> 1, wn = wave & 1;
;   f32x16 acc[2][NT];
; #pragma unroll
;   for (int a = 0; a < 2; ++a)
; #pragma unroll
;     for (int b = 0; b < NT; ++b) acc[a][b] = fzero();
;   u32x4 ra[4], rb[NB8];
;   const int lrow = tid >> 3, lch = tid & 7;
;   const u16* Ap = A + (size_t)(m0 + lrow) * lda + lch * 8;
;   const u16* Bp = Bt + (size_t)(n0 + lrow) * ldb + lch * 8;
; #pragma unroll
;   for (int i = 0; i < 4; ++i) ra[i] = *(const u32x4*)(Ap + (size_t)(32 * i) * lda);
; #pragma unroll
;   for (int i = 0; i < NB8; ++i) rb[i] = *(const u32x4*)(Bp + (size_t)(32 * i) * ldb);
;     ...
;       for (int q = lb; q < 64 * ntn; q += nlb) {
;         const int tm = x * 64 + q / ntn, tn = q % ntn;
;         gemm_tile<NTM>(A, lda, Bt, ldb, K, tm * 128, tn * (64 * NTM), epi, smem);
.LBB0_96:
	s_and_b32 s8, s79, 0xffff
	s_mul_i32 s8, s8, 0xaaab
	s_lshr_b32 s8, s8, 18
	s_add_i32 s9, s34, s8
	s_mul_i32 s8, s8, 6
	s_sub_i32 s10, s79, s8
	s_lshl_b32 s11, s9, 7
	s_lshl_b32 s8, s10, 8
	v_or_b32_e32 v192, s11, v186
	s_and_b32 s12, s8, 0xff00
	v_lshlrev_b64 v[0:1], 11, v[192:193]
	v_lshl_add_u64 v[2:3], v[194:195], 0, v[0:1]
	v_or_b32_e32 v4, s12, v186
	v_lshlrev_b32_e32 v192, 11, v4
	v_add_co_u32_e32 v4, vcc, s35, v2
	v_lshl_add_u64 v[200:201], v[198:199], 0, v[0:1]
	s_nop 0
	v_addc_co_u32_e32 v5, vcc, 0, v3, vcc
	global_load_dwordx4 v[128:131], v[2:3], off
	global_load_dwordx4 v[132:135], v[4:5], off
	v_add_co_u32_e32 v4, vcc, s36, v2
	v_lshl_add_u64 v[202:203], v[198:199], 0, v[192:193]
	s_nop 0
	v_addc_co_u32_e32 v5, vcc, 0, v3, vcc
	v_add_co_u32_e32 v2, vcc, s37, v2
	s_mov_b64 s[8:9], 0
	s_nop 0
	v_addc_co_u32_e32 v3, vcc, 0, v3, vcc
	global_load_dwordx4 v[136:139], v[4:5], off
	global_load_dwordx4 v[140:143], v[2:3], off
	v_lshl_add_u64 v[2:3], v[196:197], 0, v[192:193]
	v_add_co_u32_e32 v4, vcc, s35, v2
	v_mov_b32_e32 v0, 0
	s_nop 0
	v_addc_co_u32_e32 v5, vcc, 0, v3, vcc
	global_load_dwordx4 v[144:147], v[2:3], off
	global_load_dwordx4 v[148:151], v[4:5], off
	v_add_co_u32_e32 v4, vcc, s36, v2
	v_mov_b32_e32 v1, v193
	s_nop 0
	v_addc_co_u32_e32 v5, vcc, 0, v3, vcc
	v_add_co_u32_e32 v6, vcc, s37, v2
	v_mov_b32_e32 v8, v193
	s_nop 0
	v_addc_co_u32_e32 v7, vcc, 0, v3, vcc
	global_load_dwordx4 v[152:155], v[4:5], off
	global_load_dwordx4 v[156:159], v[6:7], off
	v_add_co_u32_e32 v4, vcc, s38, v2
	v_mov_b32_e32 v9, v193
	s_nop 0
	v_addc_co_u32_e32 v5, vcc, 0, v3, vcc
	v_add_co_u32_e32 v6, vcc, 0x50000, v2
	v_mov_b32_e32 v10, v193
	s_nop 0
	v_addc_co_u32_e32 v7, vcc, 0, v3, vcc
	global_load_dwordx4 v[160:163], v[4:5], off
	global_load_dwordx4 v[164:167], v[6:7], off
	v_add_co_u32_e32 v4, vcc, 0x60000, v2
	v_mov_b32_e32 v6, v193
	s_nop 0
	v_addc_co_u32_e32 v5, vcc, 0, v3, vcc
	v_add_co_u32_e32 v2, vcc, 0x70000, v2
	v_mov_b32_e32 v7, v193
	s_nop 0
	v_addc_co_u32_e32 v3, vcc, 0, v3, vcc
	global_load_dwordx4 v[168:171], v[4:5], off
	global_load_dwordx4 v[172:175], v[2:3], off
	v_mov_b32_e32 v2, v193
	v_mov_b32_e32 v3, v193
	v_mov_b32_e32 v4, v193
	v_mov_b32_e32 v5, v193
	v_mov_b32_e32 v11, v193
	v_mov_b32_e32 v12, v193
	v_mov_b32_e32 v13, v193
	v_mov_b32_e32 v14, v193
	v_mov_b32_e32 v15, v193
	v_mov_b32_e32 v16, 0
	v_mov_b32_e32 v17, v193
	v_mov_b32_e32 v18, v193
	v_mov_b32_e32 v19, v193
	v_mov_b32_e32 v20, v193
	v_mov_b32_e32 v21, v193
	v_mov_b32_e32 v22, v193
	v_mov_b32_e32 v23, v193
	v_mov_b32_e32 v24, v193
	v_mov_b32_e32 v25, v193
	v_mov_b32_e32 v26, v193
	v_mov_b32_e32 v27, v193
	v_mov_b32_e32 v28, v193
	v_mov_b32_e32 v29, v193
	v_mov_b32_e32 v30, v193
	v_mov_b32_e32 v31, v193
	v_mov_b32_e32 v32, 0
	v_mov_b32_e32 v33, v193
	v_mov_b32_e32 v34, v193
	v_mov_b32_e32 v35, v193
	v_mov_b32_e32 v36, v193
	v_mov_b32_e32 v37, v193
	v_mov_b32_e32 v38, v193
	v_mov_b32_e32 v39, v193
	v_mov_b32_e32 v40, v193
	v_mov_b32_e32 v41, v193
	v_mov_b32_e32 v42, v193
	v_mov_b32_e32 v43, v193
	v_mov_b32_e32 v44, v193
	v_mov_b32_e32 v45, v193
	v_mov_b32_e32 v46, v193
	v_mov_b32_e32 v47, v193
	v_mov_b32_e32 v48, 0
	v_mov_b32_e32 v49, v193
	v_mov_b32_e32 v50, v193
	v_mov_b32_e32 v51, v193
	v_mov_b32_e32 v52, v193
	v_mov_b32_e32 v53, v193
	v_mov_b32_e32 v54, v193
	v_mov_b32_e32 v55, v193
	v_mov_b32_e32 v56, v193
	v_mov_b32_e32 v57, v193
	v_mov_b32_e32 v58, v193
	v_mov_b32_e32 v59, v193
	v_mov_b32_e32 v60, v193
	v_mov_b32_e32 v61, v193
	v_mov_b32_e32 v62, v193
	v_mov_b32_e32 v63, v193
	v_mov_b32_e32 v64, 0
	v_mov_b32_e32 v65, v193
	v_mov_b32_e32 v66, v193
	v_mov_b32_e32 v67, v193
	v_mov_b32_e32 v68, v193
	v_mov_b32_e32 v69, v193
	v_mov_b32_e32 v70, v193
	v_mov_b32_e32 v71, v193
	v_mov_b32_e32 v72, v193
	v_mov_b32_e32 v73, v193
	v_mov_b32_e32 v74, v193
	v_mov_b32_e32 v75, v193
	v_mov_b32_e32 v76, v193
	v_mov_b32_e32 v77, v193
	v_mov_b32_e32 v78, v193
	v_mov_b32_e32 v79, v193
	v_mov_b32_e32 v80, 0
	v_mov_b32_e32 v81, v193
	v_mov_b32_e32 v82, v193
	v_mov_b32_e32 v83, v193
	v_mov_b32_e32 v84, v193
	v_mov_b32_e32 v85, v193
	v_mov_b32_e32 v86, v193
	v_mov_b32_e32 v87, v193
	v_mov_b32_e32 v88, v193
	v_mov_b32_e32 v89, v193
	v_mov_b32_e32 v90, v193
	v_mov_b32_e32 v91, v193
	v_mov_b32_e32 v92, v193
	v_mov_b32_e32 v93, v193
	v_mov_b32_e32 v94, v193
	v_mov_b32_e32 v95, v193
	v_mov_b32_e32 v96, 0
	v_mov_b32_e32 v97, v193
	v_mov_b32_e32 v98, v193
	v_mov_b32_e32 v99, v193
	v_mov_b32_e32 v100, v193
	v_mov_b32_e32 v101, v193
	v_mov_b32_e32 v102, v193
	v_mov_b32_e32 v103, v193
	v_mov_b32_e32 v104, v193
	v_mov_b32_e32 v105, v193
	v_mov_b32_e32 v106, v193
	v_mov_b32_e32 v107, v193
	v_mov_b32_e32 v108, v193
	v_mov_b32_e32 v109, v193
	v_mov_b32_e32 v110, v193
	v_mov_b32_e32 v111, v193
	v_mov_b32_e32 v112, 0
	v_mov_b32_e32 v113, v193
	v_mov_b32_e32 v114, v193
	v_mov_b32_e32 v115, v193
	v_mov_b32_e32 v116, v193
	v_mov_b32_e32 v117, v193
	v_mov_b32_e32 v118, v193
	v_mov_b32_e32 v119, v193
	v_mov_b32_e32 v120, v193
	v_mov_b32_e32 v121, v193
	v_mov_b32_e32 v122, v193
	v_mov_b32_e32 v123, v193
	v_mov_b32_e32 v124, v193
	v_mov_b32_e32 v125, v193
	v_mov_b32_e32 v126, v193
	v_mov_b32_e32 v127, v193
	.p2align	6

; DI f32x16 fzero() { f32x16 z; for (int i = 0; i < 16; ++i) z[i] = 0.f; return z; }
; template <int NT, class Epi>
; DI void gemm_tile(const u16* __restrict__ A, int lda, const u16* __restrict__ Bt, int ldb, int K, int m0, int n0, const Epi& epi, char* smem) {
;   constexpr int BN = 64 * NT, NB8 = 2 * NT;
;   u16* As = (u16*)smem;
;   u16* Bs = As + 128 * 72;
;   const int tid = threadIdx.x, lane = tid & 63, wave = tid >> 6, r = lane & 31, h = lane >> 5;
;   const int wm = wave >> 1, wn = wave & 1;
;   f32x16 acc[2][NT];
; #pragma unroll
;   for (int a = 0; a < 2; ++a)
; #pragma unroll
;     for (int b = 0; b < NT; ++b) acc[a][b] = fzero();
;   u32x4 ra[4], rb[NB8];
;   const int lrow = tid >> 3, lch = tid & 7;
;   const u16* Ap = A + (size_t)(m0 + lrow) * lda + lch * 8;
;   const u16* Bp = Bt + (size_t)(n0 + lrow) * ldb + lch * 8;
; #pragma unroll
;   for (int i = 0; i < 4; ++i) ra[i] = *(const u32x4*)(Ap + (size_t)(32 * i) * lda);
; #pragma unroll
;   for (int i = 0; i < NB8; ++i) rb[i] = *(const u32x4*)(Bp + (size_t)(32 * i) * ldb);
;     ...
;       for (int q = lb; q < 64 * ntn; q += nlb) {
;         const int tm = x * 64 + q / ntn, tn = q % ntn;
;         gemm_tile<NTM>(A, lda, Bt, ldb, K, tm * 128, tn * (64 * NTM), epi, smem);
.LBB0_421:
	s_lshr_b32 s16, s58, 2
	v_lshl_add_u32 v192, s16, 7, v185
	s_lshl_b32 s17, s18, 11
	s_or_b32 s16, s16, s3
	v_lshlrev_b64 v[0:1], 11, v[192:193]
	s_and_b32 s17, s17, 0x180000
	s_lshl_b32 s59, s16, 7
	v_lshl_add_u64 v[202:203], v[200:201], 0, v[0:1]
	v_or_b32_e32 v192, s17, v187
	s_lshl_b32 s16, s58, 8
	v_or_b32_e32 v0, s59, v186
	v_lshl_add_u64 v[204:205], v[200:201], 0, v[192:193]
	s_and_b32 s60, s16, 0x300
	v_lshlrev_b32_e32 v192, 11, v0
	v_lshl_add_u64 v[0:1], v[196:197], 0, v[192:193]
	v_or_b32_e32 v2, s60, v186
	v_lshlrev_b32_e32 v192, 11, v2
	v_add_co_u32_e32 v2, vcc, s20, v0
	s_mov_b64 s[16:17], 0
	s_nop 0
	v_addc_co_u32_e32 v3, vcc, 0, v1, vcc
	global_load_dwordx4 v[128:131], v[0:1], off
	global_load_dwordx4 v[132:135], v[2:3], off
	v_add_co_u32_e32 v2, vcc, s21, v0
	v_mov_b32_e32 v6, v193
	s_nop 0
	v_addc_co_u32_e32 v3, vcc, 0, v1, vcc
	v_add_co_u32_e32 v0, vcc, s22, v0
	v_mov_b32_e32 v7, v193
	s_nop 0
	v_addc_co_u32_e32 v1, vcc, 0, v1, vcc
	global_load_dwordx4 v[136:139], v[2:3], off
	global_load_dwordx4 v[140:143], v[0:1], off
	v_lshl_add_u64 v[0:1], v[198:199], 0, v[192:193]
	v_add_co_u32_e32 v2, vcc, s20, v0
	v_mov_b32_e32 v8, v193
	s_nop 0
	v_addc_co_u32_e32 v3, vcc, 0, v1, vcc
	global_load_dwordx4 v[144:147], v[0:1], off
	global_load_dwordx4 v[148:151], v[2:3], off
	v_add_co_u32_e32 v2, vcc, s21, v0
	v_mov_b32_e32 v9, v193
	s_nop 0
	v_addc_co_u32_e32 v3, vcc, 0, v1, vcc
	v_add_co_u32_e32 v4, vcc, s22, v0
	v_mov_b32_e32 v10, v193
	s_nop 0
	v_addc_co_u32_e32 v5, vcc, 0, v1, vcc
	global_load_dwordx4 v[152:155], v[2:3], off
	global_load_dwordx4 v[156:159], v[4:5], off
	v_add_co_u32_e32 v2, vcc, s23, v0
	v_mov_b32_e32 v11, v193
	s_nop 0
	v_addc_co_u32_e32 v3, vcc, 0, v1, vcc
	v_add_co_u32_e32 v4, vcc, 0x50000, v0
	v_mov_b32_e32 v12, v193
	s_nop 0
	v_addc_co_u32_e32 v5, vcc, 0, v1, vcc
	global_load_dwordx4 v[160:163], v[2:3], off
	global_load_dwordx4 v[164:167], v[4:5], off
	v_add_co_u32_e32 v2, vcc, 0x60000, v0
	v_mov_b32_e32 v4, v193
	s_nop 0
	v_addc_co_u32_e32 v3, vcc, 0, v1, vcc
	v_add_co_u32_e32 v0, vcc, 0x70000, v0
	v_mov_b32_e32 v5, v193
	s_nop 0
	v_addc_co_u32_e32 v1, vcc, 0, v1, vcc
	global_load_dwordx4 v[168:171], v[2:3], off
	global_load_dwordx4 v[172:175], v[0:1], off
	v_mov_b32_e32 v0, 0
	v_mov_b32_e32 v1, v193
	v_mov_b32_e32 v2, v193
	v_mov_b32_e32 v3, v193
	v_mov_b32_e32 v13, v193
	v_mov_b32_e32 v14, v193
	v_mov_b32_e32 v15, v193
	v_mov_b32_e32 v16, 0
	v_mov_b32_e32 v17, v193
	v_mov_b32_e32 v18, v193
	v_mov_b32_e32 v19, v193
	v_mov_b32_e32 v20, v193
	v_mov_b32_e32 v21, v193
	v_mov_b32_e32 v22, v193
	v_mov_b32_e32 v23, v193
	v_mov_b32_e32 v24, v193
	v_mov_b32_e32 v25, v193
	v_mov_b32_e32 v26, v193
	v_mov_b32_e32 v27, v193
	v_mov_b32_e32 v28, v193
	v_mov_b32_e32 v29, v193
	v_mov_b32_e32 v30, v193
	v_mov_b32_e32 v31, v193
	v_mov_b32_e32 v32, 0
	v_mov_b32_e32 v33, v193
	v_mov_b32_e32 v34, v193
	v_mov_b32_e32 v35, v193
	v_mov_b32_e32 v36, v193
	v_mov_b32_e32 v37, v193
	v_mov_b32_e32 v38, v193
	v_mov_b32_e32 v39, v193
	v_mov_b32_e32 v40, v193
	v_mov_b32_e32 v41, v193
	v_mov_b32_e32 v42, v193
	v_mov_b32_e32 v43, v193
	v_mov_b32_e32 v44, v193
	v_mov_b32_e32 v45, v193
	v_mov_b32_e32 v46, v193
	v_mov_b32_e32 v47, v193
	v_mov_b32_e32 v48, 0
	v_mov_b32_e32 v49, v193
	v_mov_b32_e32 v50, v193
	v_mov_b32_e32 v51, v193
	v_mov_b32_e32 v52, v193
	v_mov_b32_e32 v53, v193
	v_mov_b32_e32 v54, v193
	v_mov_b32_e32 v55, v193
	v_mov_b32_e32 v56, v193
	v_mov_b32_e32 v57, v193
	v_mov_b32_e32 v58, v193
	v_mov_b32_e32 v59, v193
	v_mov_b32_e32 v60, v193
	v_mov_b32_e32 v61, v193
	v_mov_b32_e32 v62, v193
	v_mov_b32_e32 v63, v193
	v_mov_b32_e32 v64, 0
	v_mov_b32_e32 v65, v193
	v_mov_b32_e32 v66, v193
	v_mov_b32_e32 v67, v193
	v_mov_b32_e32 v68, v193
	v_mov_b32_e32 v69, v193
	v_mov_b32_e32 v70, v193
	v_mov_b32_e32 v71, v193
	v_mov_b32_e32 v72, v193
	v_mov_b32_e32 v73, v193
	v_mov_b32_e32 v74, v193
	v_mov_b32_e32 v75, v193
	v_mov_b32_e32 v76, v193
	v_mov_b32_e32 v77, v193
	v_mov_b32_e32 v78, v193
	v_mov_b32_e32 v79, v193
	s_waitcnt vmcnt(15)
	v_mov_b32_e32 v80, 0
	v_mov_b32_e32 v81, v193
	v_mov_b32_e32 v82, v193
	v_mov_b32_e32 v83, v193
	s_waitcnt vmcnt(12)
	v_mov_b32_e32 v84, v193
	v_mov_b32_e32 v85, v193
	v_mov_b32_e32 v86, v193
	v_mov_b32_e32 v87, v193
	v_mov_b32_e32 v88, v193
	v_mov_b32_e32 v89, v193
	v_mov_b32_e32 v90, v193
	v_mov_b32_e32 v91, v193
	v_mov_b32_e32 v92, v193
	v_mov_b32_e32 v93, v193
	v_mov_b32_e32 v94, v193
	v_mov_b32_e32 v95, v193
	v_mov_b32_e32 v96, 0
	v_mov_b32_e32 v97, v193
	v_mov_b32_e32 v98, v193
	v_mov_b32_e32 v99, v193
	v_mov_b32_e32 v100, v193
	v_mov_b32_e32 v101, v193
	v_mov_b32_e32 v102, v193
	v_mov_b32_e32 v103, v193
	v_mov_b32_e32 v104, v193
	v_mov_b32_e32 v105, v193
	v_mov_b32_e32 v106, v193
	v_mov_b32_e32 v107, v193
	v_mov_b32_e32 v108, v193
	v_mov_b32_e32 v109, v193
	v_mov_b32_e32 v110, v193
	v_mov_b32_e32 v111, v193
	v_mov_b32_e32 v112, 0
	v_mov_b32_e32 v113, v193
	v_mov_b32_e32 v114, v193
	v_mov_b32_e32 v115, v193
	v_mov_b32_e32 v116, v193
	v_mov_b32_e32 v117, v193
	v_mov_b32_e32 v118, v193
	v_mov_b32_e32 v119, v193
	v_mov_b32_e32 v120, v193
	v_mov_b32_e32 v121, v193
	v_mov_b32_e32 v122, v193
	v_mov_b32_e32 v123, v193
	v_mov_b32_e32 v124, v193
	v_mov_b32_e32 v125, v193
	v_mov_b32_e32 v126, v193
	v_mov_b32_e32 v127, v193
	.p2align	6

; DI f32x16 fzero() { f32x16 z; for (int i = 0; i < 16; ++i) z[i] = 0.f; return z; }
; template <int NT, class Epi>
; DI void gemm_tile(const u16* __restrict__ A, int lda, const u16* __restrict__ Bt, int ldb, int K, int m0, int n0, const Epi& epi, char* smem) {
;   constexpr int BN = 64 * NT, NB8 = 2 * NT;
;   u16* As = (u16*)smem;
;   u16* Bs = As + 128 * 72;
;   const int tid = threadIdx.x, lane = tid & 63, wave = tid >> 6, r = lane & 31, h = lane >> 5;
;   const int wm = wave >> 1, wn = wave & 1;
;   f32x16 acc[2][NT];
; #pragma unroll
;   for (int a = 0; a < 2; ++a)
; #pragma unroll
;     for (int b = 0; b < NT; ++b) acc[a][b] = fzero();
;   u32x4 ra[4], rb[NB8];
;   const int lrow = tid >> 3, lch = tid & 7;
;   const u16* Ap = A + (size_t)(m0 + lrow) * lda + lch * 8;
;   const u16* Bp = Bt + (size_t)(n0 + lrow) * ldb + lch * 8;
; #pragma unroll
;   for (int i = 0; i < 4; ++i) ra[i] = *(const u32x4*)(Ap + (size_t)(32 * i) * lda);
; #pragma unroll
;   for (int i = 0; i < NB8; ++i) rb[i] = *(const u32x4*)(Bp + (size_t)(32 * i) * ldb);
;     ...
;       for (int q = lb; q < 64 * ntn; q += nlb) {
;         const int tm = x * 64 + q / ntn, tn = q % ntn;
;         gemm_tile<NTM>(A, lda, Bt, ldb, K, tm * 128, tn * (64 * NTM), epi, smem);
.LBB0_454:
	s_bfe_u32 s16, s44, 0x60002
	s_lshl_b32 s17, s16, 7
	v_add_lshl_u32 v192, v185, s17, 11
	s_lshl_b32 s17, s18, 11
	s_or_b32 s16, s16, s3
	s_and_b32 s17, s17, 0x180000
	s_lshl_b32 s45, s16, 7
	v_lshl_add_u64 v[202:203], v[200:201], 0, v[192:193]
	v_or_b32_e32 v192, s17, v187
	s_lshl_b32 s16, s44, 8
	v_or_b32_e32 v0, s45, v186
	v_lshl_add_u64 v[204:205], v[200:201], 0, v[192:193]
	s_and_b32 s58, s16, 0x300
	v_lshlrev_b32_e32 v192, 11, v0
	v_lshl_add_u64 v[0:1], v[196:197], 0, v[192:193]
	v_or_b32_e32 v2, s58, v186
	v_lshlrev_b32_e32 v192, 11, v2
	v_add_co_u32_e32 v2, vcc, s20, v0
	s_mov_b64 s[16:17], 0
	s_nop 0
	v_addc_co_u32_e32 v3, vcc, 0, v1, vcc
	global_load_dwordx4 v[128:131], v[0:1], off
	global_load_dwordx4 v[132:135], v[2:3], off
	v_add_co_u32_e32 v2, vcc, s21, v0
	v_mov_b32_e32 v6, v193
	s_nop 0
	v_addc_co_u32_e32 v3, vcc, 0, v1, vcc
	v_add_co_u32_e32 v0, vcc, s22, v0
	v_mov_b32_e32 v7, v193
	s_nop 0
	v_addc_co_u32_e32 v1, vcc, 0, v1, vcc
	global_load_dwordx4 v[136:139], v[2:3], off
	global_load_dwordx4 v[140:143], v[0:1], off
	v_lshl_add_u64 v[0:1], v[198:199], 0, v[192:193]
	v_add_co_u32_e32 v2, vcc, s20, v0
	v_mov_b32_e32 v8, v193
	s_nop 0
	v_addc_co_u32_e32 v3, vcc, 0, v1, vcc
	global_load_dwordx4 v[144:147], v[0:1], off
	global_load_dwordx4 v[148:151], v[2:3], off
	v_add_co_u32_e32 v2, vcc, s21, v0
	v_mov_b32_e32 v9, v193
	s_nop 0
	v_addc_co_u32_e32 v3, vcc, 0, v1, vcc
	v_add_co_u32_e32 v4, vcc, s22, v0
	v_mov_b32_e32 v10, v193
	s_nop 0
	v_addc_co_u32_e32 v5, vcc, 0, v1, vcc
	global_load_dwordx4 v[152:155], v[2:3], off
	global_load_dwordx4 v[156:159], v[4:5], off
	v_add_co_u32_e32 v2, vcc, s23, v0
	v_mov_b32_e32 v11, v193
	s_nop 0
	v_addc_co_u32_e32 v3, vcc, 0, v1, vcc
	v_add_co_u32_e32 v4, vcc, 0x50000, v0
	v_mov_b32_e32 v12, v193
	s_nop 0
	v_addc_co_u32_e32 v5, vcc, 0, v1, vcc
	global_load_dwordx4 v[160:163], v[2:3], off
	global_load_dwordx4 v[164:167], v[4:5], off
	v_add_co_u32_e32 v2, vcc, 0x60000, v0
	v_mov_b32_e32 v4, v193
	s_nop 0
	v_addc_co_u32_e32 v3, vcc, 0, v1, vcc
	v_add_co_u32_e32 v0, vcc, 0x70000, v0
	v_mov_b32_e32 v5, v193
	s_nop 0
	v_addc_co_u32_e32 v1, vcc, 0, v1, vcc
	global_load_dwordx4 v[168:171], v[2:3], off
	global_load_dwordx4 v[172:175], v[0:1], off
	v_mov_b32_e32 v0, 0
	v_mov_b32_e32 v1, v193
	v_mov_b32_e32 v2, v193
	v_mov_b32_e32 v3, v193
	v_mov_b32_e32 v13, v193
	v_mov_b32_e32 v14, v193
	v_mov_b32_e32 v15, v193
	v_mov_b32_e32 v16, 0
	v_mov_b32_e32 v17, v193
	v_mov_b32_e32 v18, v193
	v_mov_b32_e32 v19, v193
	v_mov_b32_e32 v20, v193
	v_mov_b32_e32 v21, v193
	v_mov_b32_e32 v22, v193
	v_mov_b32_e32 v23, v193
	v_mov_b32_e32 v24, v193
	v_mov_b32_e32 v25, v193
	v_mov_b32_e32 v26, v193
	v_mov_b32_e32 v27, v193
	v_mov_b32_e32 v28, v193
	v_mov_b32_e32 v29, v193
	v_mov_b32_e32 v30, v193
	v_mov_b32_e32 v31, v193
	v_mov_b32_e32 v32, 0
	v_mov_b32_e32 v33, v193
	v_mov_b32_e32 v34, v193
	v_mov_b32_e32 v35, v193
	v_mov_b32_e32 v36, v193
	v_mov_b32_e32 v37, v193
	v_mov_b32_e32 v38, v193
	v_mov_b32_e32 v39, v193
	v_mov_b32_e32 v40, v193
	v_mov_b32_e32 v41, v193
	v_mov_b32_e32 v42, v193
	v_mov_b32_e32 v43, v193
	v_mov_b32_e32 v44, v193
	v_mov_b32_e32 v45, v193
	v_mov_b32_e32 v46, v193
	v_mov_b32_e32 v47, v193
	v_mov_b32_e32 v48, 0
	v_mov_b32_e32 v49, v193
	v_mov_b32_e32 v50, v193
	v_mov_b32_e32 v51, v193
	v_mov_b32_e32 v52, v193
	v_mov_b32_e32 v53, v193
	v_mov_b32_e32 v54, v193
	v_mov_b32_e32 v55, v193
	v_mov_b32_e32 v56, v193
	v_mov_b32_e32 v57, v193
	v_mov_b32_e32 v58, v193
	v_mov_b32_e32 v59, v193
	v_mov_b32_e32 v60, v193
	v_mov_b32_e32 v61, v193
	v_mov_b32_e32 v62, v193
	v_mov_b32_e32 v63, v193
	v_mov_b32_e32 v64, 0
	v_mov_b32_e32 v65, v193
	v_mov_b32_e32 v66, v193
	v_mov_b32_e32 v67, v193
	v_mov_b32_e32 v68, v193
	v_mov_b32_e32 v69, v193
	v_mov_b32_e32 v70, v193
	v_mov_b32_e32 v71, v193
	v_mov_b32_e32 v72, v193
	v_mov_b32_e32 v73, v193
	v_mov_b32_e32 v74, v193
	v_mov_b32_e32 v75, v193
	v_mov_b32_e32 v76, v193
	v_mov_b32_e32 v77, v193
	v_mov_b32_e32 v78, v193
	v_mov_b32_e32 v79, v193
	s_waitcnt vmcnt(15)
	v_mov_b32_e32 v80, 0
	v_mov_b32_e32 v81, v193
	v_mov_b32_e32 v82, v193
	v_mov_b32_e32 v83, v193
	s_waitcnt vmcnt(12)
	v_mov_b32_e32 v84, v193
	v_mov_b32_e32 v85, v193
	v_mov_b32_e32 v86, v193
	v_mov_b32_e32 v87, v193
	v_mov_b32_e32 v88, v193
	v_mov_b32_e32 v89, v193
	v_mov_b32_e32 v90, v193
	v_mov_b32_e32 v91, v193
	v_mov_b32_e32 v92, v193
	v_mov_b32_e32 v93, v193
	v_mov_b32_e32 v94, v193
	v_mov_b32_e32 v95, v193
	v_mov_b32_e32 v96, 0
	v_mov_b32_e32 v97, v193
	v_mov_b32_e32 v98, v193
	v_mov_b32_e32 v99, v193
	v_mov_b32_e32 v100, v193
	v_mov_b32_e32 v101, v193
	v_mov_b32_e32 v102, v193
	v_mov_b32_e32 v103, v193
	v_mov_b32_e32 v104, v193
	v_mov_b32_e32 v105, v193
	v_mov_b32_e32 v106, v193
	v_mov_b32_e32 v107, v193
	v_mov_b32_e32 v108, v193
	v_mov_b32_e32 v109, v193
	v_mov_b32_e32 v110, v193
	v_mov_b32_e32 v111, v193
	v_mov_b32_e32 v112, 0
	v_mov_b32_e32 v113, v193
	v_mov_b32_e32 v114, v193
	v_mov_b32_e32 v115, v193
	v_mov_b32_e32 v116, v193
	v_mov_b32_e32 v117, v193
	v_mov_b32_e32 v118, v193
	v_mov_b32_e32 v119, v193
	v_mov_b32_e32 v120, v193
	v_mov_b32_e32 v121, v193
	v_mov_b32_e32 v122, v193
	v_mov_b32_e32 v123, v193
	v_mov_b32_e32 v124, v193
	v_mov_b32_e32 v125, v193
	v_mov_b32_e32 v126, v193
	v_mov_b32_e32 v127, v193
	.p2align	6

; DI f32x16 fzero() { f32x16 z; for (int i = 0; i < 16; ++i) z[i] = 0.f; return z; }
; template <int NT, class Epi>
; DI void gemm_tile(const u16* __restrict__ A, int lda, const u16* __restrict__ Bt, int ldb, int K, int m0, int n0, const Epi& epi, char* smem) {
;   constexpr int BN = 64 * NT, NB8 = 2 * NT;
;   u16* As = (u16*)smem;
;   u16* Bs = As + 128 * 72;
;   const int tid = threadIdx.x, lane = tid & 63, wave = tid >> 6, r = lane & 31, h = lane >> 5;
;   const int wm = wave >> 1, wn = wave & 1;
;   f32x16 acc[2][NT];
; #pragma unroll
;   for (int a = 0; a < 2; ++a)
; #pragma unroll
;     for (int b = 0; b < NT; ++b) acc[a][b] = fzero();
;   u32x4 ra[4], rb[NB8];
;   const int lrow = tid >> 3, lch = tid & 7;
;   const u16* Ap = A + (size_t)(m0 + lrow) * lda + lch * 8;
;   const u16* Bp = Bt + (size_t)(n0 + lrow) * ldb + lch * 8;
; #pragma unroll
;   for (int i = 0; i < 4; ++i) ra[i] = *(const u32x4*)(Ap + (size_t)(32 * i) * lda);
; #pragma unroll
;   for (int i = 0; i < NB8; ++i) rb[i] = *(const u32x4*)(Bp + (size_t)(32 * i) * ldb);
;     ...
;       for (int q = lb; q < 64 * ntn; q += nlb) {
;         const int tm = x * 64 + q / ntn, tn = q % ntn;
;         gemm_tile<NTM>(A, lda, Bt, ldb, K, tm * 128, tn * (64 * NTM), epi, smem);
.LBB0_519:
	s_and_b32 s12, s41, 0xffff
	s_mulk_i32 s12, 0x4ec5
	s_lshr_b32 s12, s12, 18
	s_add_i32 s13, s3, s12
	s_lshl_b32 s14, s13, 7
	v_or_b32_e32 v0, s14, v186
	v_lshlrev_b32_e32 v200, 11, v0
	v_lshl_add_u64 v[0:1], v[202:203], 0, v[200:201]
	s_mul_i32 s12, s12, 13
	v_add_co_u32_e32 v4, vcc, s22, v0
	s_sub_i32 s12, s41, s12
	s_nop 0
	v_addc_co_u32_e32 v5, vcc, 0, v1, vcc
	s_lshl_b32 s12, s12, 8
	global_load_dwordx4 v[128:131], v[0:1], off
	global_load_dwordx4 v[132:135], v[4:5], off
	v_add_co_u32_e32 v4, vcc, s23, v0
	s_and_b32 s15, s12, 0xff00
	s_nop 0
	v_addc_co_u32_e32 v5, vcc, 0, v1, vcc
	v_or_b32_e32 v2, s15, v186
	v_add_co_u32_e32 v0, vcc, s24, v0
	v_lshlrev_b32_e32 v2, 11, v2
	v_mov_b32_e32 v3, v201
	v_addc_co_u32_e32 v1, vcc, 0, v1, vcc
	global_load_dwordx4 v[136:139], v[4:5], off
	global_load_dwordx4 v[140:143], v[0:1], off
	v_lshl_add_u64 v[0:1], v[204:205], 0, v[2:3]
	v_add_co_u32_e32 v4, vcc, s22, v0
	v_lshl_add_u64 v[208:209], v[206:207], 0, v[200:201]
	s_nop 0
	v_addc_co_u32_e32 v5, vcc, 0, v1, vcc
	global_load_dwordx4 v[144:147], v[0:1], off
	global_load_dwordx4 v[148:151], v[4:5], off
	v_add_co_u32_e32 v4, vcc, s23, v0
	v_lshl_add_u64 v[210:211], v[206:207], 0, v[2:3]
	s_nop 0
	v_addc_co_u32_e32 v5, vcc, 0, v1, vcc
	v_add_co_u32_e32 v6, vcc, s24, v0
	s_mov_b64 s[12:13], 0
	s_nop 0
	v_addc_co_u32_e32 v7, vcc, 0, v1, vcc
	global_load_dwordx4 v[152:155], v[4:5], off
	global_load_dwordx4 v[156:159], v[6:7], off
	v_add_co_u32_e32 v4, vcc, s25, v0
	v_mov_b32_e32 v2, v201
	s_nop 0
	v_addc_co_u32_e32 v5, vcc, 0, v1, vcc
	v_add_co_u32_e32 v6, vcc, 0x50000, v0
	v_mov_b32_e32 v8, v201
	s_nop 0
	v_addc_co_u32_e32 v7, vcc, 0, v1, vcc
	global_load_dwordx4 v[160:163], v[4:5], off
	global_load_dwordx4 v[164:167], v[6:7], off
	v_add_co_u32_e32 v4, vcc, 0x60000, v0
	v_mov_b32_e32 v6, v201
	s_nop 0
	v_addc_co_u32_e32 v5, vcc, 0, v1, vcc
	v_add_co_u32_e32 v0, vcc, 0x70000, v0
	v_mov_b32_e32 v7, v201
	s_nop 0
	v_addc_co_u32_e32 v1, vcc, 0, v1, vcc
	global_load_dwordx4 v[168:171], v[4:5], off
	global_load_dwordx4 v[172:175], v[0:1], off
	v_mov_b32_e32 v0, 0
	v_mov_b32_e32 v1, v201
	v_mov_b32_e32 v4, v201
	v_mov_b32_e32 v5, v201
	v_mov_b32_e32 v9, v201
	v_mov_b32_e32 v10, v201
	v_mov_b32_e32 v11, v201
	v_mov_b32_e32 v12, v201
	v_mov_b32_e32 v13, v201
	v_mov_b32_e32 v14, v201
	v_mov_b32_e32 v15, v201
	v_mov_b32_e32 v16, 0
	v_mov_b32_e32 v17, v201
	v_mov_b32_e32 v18, v201
	v_mov_b32_e32 v19, v201
	v_mov_b32_e32 v20, v201
	v_mov_b32_e32 v21, v201
	v_mov_b32_e32 v22, v201
	v_mov_b32_e32 v23, v201
	v_mov_b32_e32 v24, v201
	v_mov_b32_e32 v25, v201
	v_mov_b32_e32 v26, v201
	v_mov_b32_e32 v27, v201
	v_mov_b32_e32 v28, v201
	v_mov_b32_e32 v29, v201
	v_mov_b32_e32 v30, v201
	v_mov_b32_e32 v31, v201
	v_mov_b32_e32 v32, 0
	v_mov_b32_e32 v33, v201
	v_mov_b32_e32 v34, v201
	v_mov_b32_e32 v35, v201
	v_mov_b32_e32 v36, v201
	v_mov_b32_e32 v37, v201
	v_mov_b32_e32 v38, v201
	v_mov_b32_e32 v39, v201
	v_mov_b32_e32 v40, v201
	v_mov_b32_e32 v41, v201
	v_mov_b32_e32 v42, v201
	v_mov_b32_e32 v43, v201
	v_mov_b32_e32 v44, v201
	v_mov_b32_e32 v45, v201
	v_mov_b32_e32 v46, v201
	v_mov_b32_e32 v47, v201
	v_mov_b32_e32 v48, 0
	v_mov_b32_e32 v49, v201
	v_mov_b32_e32 v50, v201
	v_mov_b32_e32 v51, v201
	v_mov_b32_e32 v52, v201
	v_mov_b32_e32 v53, v201
	v_mov_b32_e32 v54, v201
	v_mov_b32_e32 v55, v201
	v_mov_b32_e32 v56, v201
	v_mov_b32_e32 v57, v201
	v_mov_b32_e32 v58, v201
	v_mov_b32_e32 v59, v201
	v_mov_b32_e32 v60, v201
	v_mov_b32_e32 v61, v201
	v_mov_b32_e32 v62, v201
	v_mov_b32_e32 v63, v201
	v_mov_b32_e32 v64, 0
	v_mov_b32_e32 v65, v201
	v_mov_b32_e32 v66, v201
	v_mov_b32_e32 v67, v201
	v_mov_b32_e32 v68, v201
	v_mov_b32_e32 v69, v201
	v_mov_b32_e32 v70, v201
	v_mov_b32_e32 v71, v201
	v_mov_b32_e32 v72, v201
	v_mov_b32_e32 v73, v201
	v_mov_b32_e32 v74, v201
	v_mov_b32_e32 v75, v201
	v_mov_b32_e32 v76, v201
	v_mov_b32_e32 v77, v201
	v_mov_b32_e32 v78, v201
	v_mov_b32_e32 v79, v201
	s_waitcnt vmcnt(15)
	v_mov_b32_e32 v80, 0
	v_mov_b32_e32 v81, v201
	v_mov_b32_e32 v82, v201
	v_mov_b32_e32 v83, v201
	s_waitcnt vmcnt(12)
	v_mov_b32_e32 v84, v201
	v_mov_b32_e32 v85, v201
	v_mov_b32_e32 v86, v201
	v_mov_b32_e32 v87, v201
	v_mov_b32_e32 v88, v201
	v_mov_b32_e32 v89, v201
	v_mov_b32_e32 v90, v201
	v_mov_b32_e32 v91, v201
	v_mov_b32_e32 v92, v201
	v_mov_b32_e32 v93, v201
	v_mov_b32_e32 v94, v201
	v_mov_b32_e32 v95, v201
	v_mov_b32_e32 v96, 0
	v_mov_b32_e32 v97, v201
	v_mov_b32_e32 v98, v201
	v_mov_b32_e32 v99, v201
	v_mov_b32_e32 v100, v201
	v_mov_b32_e32 v101, v201
	v_mov_b32_e32 v102, v201
	v_mov_b32_e32 v103, v201
	v_mov_b32_e32 v104, v201
	v_mov_b32_e32 v105, v201
	v_mov_b32_e32 v106, v201
	v_mov_b32_e32 v107, v201
	v_mov_b32_e32 v108, v201
	v_mov_b32_e32 v109, v201
	v_mov_b32_e32 v110, v201
	v_mov_b32_e32 v111, v201
	v_mov_b32_e32 v112, 0
	v_mov_b32_e32 v113, v201
	v_mov_b32_e32 v114, v201
	v_mov_b32_e32 v115, v201
	v_mov_b32_e32 v116, v201
	v_mov_b32_e32 v117, v201
	v_mov_b32_e32 v118, v201
	v_mov_b32_e32 v119, v201
	v_mov_b32_e32 v120, v201
	v_mov_b32_e32 v121, v201
	v_mov_b32_e32 v122, v201
	v_mov_b32_e32 v123, v201
	v_mov_b32_e32 v124, v201
	v_mov_b32_e32 v125, v201
	v_mov_b32_e32 v126, v201
	v_mov_b32_e32 v127, v201
	.p2align	6

; DI f32x16 fzero() { f32x16 z; for (int i = 0; i < 16; ++i) z[i] = 0.f; return z; }
; template <int NT, class Epi>
; DI void gemm_tile(const u16* __restrict__ A, int lda, const u16* __restrict__ Bt, int ldb, int K, int m0, int n0, const Epi& epi, char* smem) {
;   constexpr int BN = 64 * NT, NB8 = 2 * NT;
;   u16* As = (u16*)smem;
;   u16* Bs = As + 128 * 72;
;   const int tid = threadIdx.x, lane = tid & 63, wave = tid >> 6, r = lane & 31, h = lane >> 5;
;   const int wm = wave >> 1, wn = wave & 1;
;   f32x16 acc[2][NT];
; #pragma unroll
;   for (int a = 0; a < 2; ++a)
; #pragma unroll
;     for (int b = 0; b < NT; ++b) acc[a][b] = fzero();
;   u32x4 ra[4], rb[NB8];
;   const int lrow = tid >> 3, lch = tid & 7;
;   const u16* Ap = A + (size_t)(m0 + lrow) * lda + lch * 8;
;   const u16* Bp = Bt + (size_t)(n0 + lrow) * ldb + lch * 8;
; #pragma unroll
;   for (int i = 0; i < 4; ++i) ra[i] = *(const u32x4*)(Ap + (size_t)(32 * i) * lda);
; #pragma unroll
;   for (int i = 0; i < NB8; ++i) rb[i] = *(const u32x4*)(Bp + (size_t)(32 * i) * ldb);
;     ...
;       for (int q = lb; q < 64 * ntn; q += nlb) {
;         const int tm = x * 64 + q / ntn, tn = q % ntn;
;         gemm_tile<NTM>(A, lda, Bt, ldb, K, tm * 128, tn * (64 * NTM), epi, smem);
.LBB0_642:
	s_lshr_b32 s20, s42, 2
	v_lshl_add_u32 v188, s20, 7, v183
	s_lshl_b32 s21, s22, 11
	s_or_b32 s20, s20, s3
	v_lshlrev_b64 v[0:1], 11, v[188:189]
	s_and_b32 s21, s21, 0x180000
	s_lshl_b32 s43, s20, 7
	v_lshl_add_u64 v[202:203], v[200:201], 0, v[0:1]
	v_or_b32_e32 v188, s21, v185
	s_lshl_b32 s20, s42, 8
	v_or_b32_e32 v0, s43, v186
	v_lshl_add_u64 v[204:205], v[200:201], 0, v[188:189]
	s_and_b32 s44, s20, 0x300
	v_lshlrev_b32_e32 v188, 11, v0
	v_lshl_add_u64 v[0:1], v[190:191], 0, v[188:189]
	v_or_b32_e32 v2, s44, v186
	v_lshlrev_b32_e32 v188, 11, v2
	v_add_co_u32_e32 v2, vcc, s24, v0
	s_mov_b64 s[20:21], 0
	s_nop 0
	v_addc_co_u32_e32 v3, vcc, 0, v1, vcc
	global_load_dwordx4 v[128:131], v[0:1], off
	global_load_dwordx4 v[132:135], v[2:3], off
	v_add_co_u32_e32 v2, vcc, s25, v0
	v_mov_b32_e32 v6, v189
	s_nop 0
	v_addc_co_u32_e32 v3, vcc, 0, v1, vcc
	v_add_co_u32_e32 v0, vcc, s26, v0
	v_mov_b32_e32 v7, v189
	s_nop 0
	v_addc_co_u32_e32 v1, vcc, 0, v1, vcc
	global_load_dwordx4 v[136:139], v[2:3], off
	global_load_dwordx4 v[140:143], v[0:1], off
	v_lshl_add_u64 v[0:1], v[194:195], 0, v[188:189]
	v_add_co_u32_e32 v2, vcc, s24, v0
	v_mov_b32_e32 v8, v189
	s_nop 0
	v_addc_co_u32_e32 v3, vcc, 0, v1, vcc
	global_load_dwordx4 v[144:147], v[0:1], off
	global_load_dwordx4 v[148:151], v[2:3], off
	v_add_co_u32_e32 v2, vcc, s25, v0
	v_mov_b32_e32 v9, v189
	s_nop 0
	v_addc_co_u32_e32 v3, vcc, 0, v1, vcc
	v_add_co_u32_e32 v4, vcc, s26, v0
	v_mov_b32_e32 v10, v189
	s_nop 0
	v_addc_co_u32_e32 v5, vcc, 0, v1, vcc
	global_load_dwordx4 v[152:155], v[2:3], off
	global_load_dwordx4 v[156:159], v[4:5], off
	v_add_co_u32_e32 v2, vcc, s27, v0
	v_mov_b32_e32 v11, v189
	s_nop 0
	v_addc_co_u32_e32 v3, vcc, 0, v1, vcc
	v_add_co_u32_e32 v4, vcc, 0x50000, v0
	v_mov_b32_e32 v12, v189
	s_nop 0
	v_addc_co_u32_e32 v5, vcc, 0, v1, vcc
	global_load_dwordx4 v[160:163], v[2:3], off
	global_load_dwordx4 v[164:167], v[4:5], off
	v_add_co_u32_e32 v2, vcc, 0x60000, v0
	v_mov_b32_e32 v4, v189
	s_nop 0
	v_addc_co_u32_e32 v3, vcc, 0, v1, vcc
	v_add_co_u32_e32 v0, vcc, 0x70000, v0
	v_mov_b32_e32 v5, v189
	s_nop 0
	v_addc_co_u32_e32 v1, vcc, 0, v1, vcc
	global_load_dwordx4 v[168:171], v[2:3], off
	global_load_dwordx4 v[172:175], v[0:1], off
	v_mov_b32_e32 v0, 0
	v_mov_b32_e32 v1, v189
	v_mov_b32_e32 v2, v189
	v_mov_b32_e32 v3, v189
	v_mov_b32_e32 v13, v189
	v_mov_b32_e32 v14, v189
	v_mov_b32_e32 v15, v189
	v_mov_b32_e32 v16, 0
	v_mov_b32_e32 v17, v189
	v_mov_b32_e32 v18, v189
	v_mov_b32_e32 v19, v189
	v_mov_b32_e32 v20, v189
	v_mov_b32_e32 v21, v189
	v_mov_b32_e32 v22, v189
	v_mov_b32_e32 v23, v189
	v_mov_b32_e32 v24, v189
	v_mov_b32_e32 v25, v189
	v_mov_b32_e32 v26, v189
	v_mov_b32_e32 v27, v189
	v_mov_b32_e32 v28, v189
	v_mov_b32_e32 v29, v189
	v_mov_b32_e32 v30, v189
	v_mov_b32_e32 v31, v189
	s_waitcnt vmcnt(13)
	v_mov_b32_e32 v32, 0
	v_mov_b32_e32 v33, v189
	v_mov_b32_e32 v34, v189
	v_mov_b32_e32 v35, v189
	s_waitcnt vmcnt(12)
	v_mov_b32_e32 v36, v189
	v_mov_b32_e32 v37, v189
	v_mov_b32_e32 v38, v189
	v_mov_b32_e32 v39, v189
	v_mov_b32_e32 v40, v189
	v_mov_b32_e32 v41, v189
	v_mov_b32_e32 v42, v189
	v_mov_b32_e32 v43, v189
	v_mov_b32_e32 v44, v189
	v_mov_b32_e32 v45, v189
	v_mov_b32_e32 v46, v189
	v_mov_b32_e32 v47, v189
	v_mov_b32_e32 v48, 0
	v_mov_b32_e32 v49, v189
	v_mov_b32_e32 v50, v189
	v_mov_b32_e32 v51, v189
	v_mov_b32_e32 v52, v189
	v_mov_b32_e32 v53, v189
	v_mov_b32_e32 v54, v189
	v_mov_b32_e32 v55, v189
	v_mov_b32_e32 v56, v189
	v_mov_b32_e32 v57, v189
	v_mov_b32_e32 v58, v189
	v_mov_b32_e32 v59, v189
	v_mov_b32_e32 v60, v189
	v_mov_b32_e32 v61, v189
	v_mov_b32_e32 v62, v189
	v_mov_b32_e32 v63, v189
	v_mov_b32_e32 v64, 0
	v_mov_b32_e32 v65, v189
	v_mov_b32_e32 v66, v189
	v_mov_b32_e32 v67, v189
	v_mov_b32_e32 v68, v189
	v_mov_b32_e32 v69, v189
	v_mov_b32_e32 v70, v189
	v_mov_b32_e32 v71, v189
	v_mov_b32_e32 v72, v189
	v_mov_b32_e32 v73, v189
	v_mov_b32_e32 v74, v189
	v_mov_b32_e32 v75, v189
	v_mov_b32_e32 v76, v189
	v_mov_b32_e32 v77, v189
	v_mov_b32_e32 v78, v189
	v_mov_b32_e32 v79, v189
	v_mov_b32_e32 v80, 0
	v_mov_b32_e32 v81, v189
	v_mov_b32_e32 v82, v189
	v_mov_b32_e32 v83, v189
	v_mov_b32_e32 v84, v189
	v_mov_b32_e32 v85, v189
	v_mov_b32_e32 v86, v189
	v_mov_b32_e32 v87, v189
	v_mov_b32_e32 v88, v189
	v_mov_b32_e32 v89, v189
	v_mov_b32_e32 v90, v189
	v_mov_b32_e32 v91, v189
	v_mov_b32_e32 v92, v189
	v_mov_b32_e32 v93, v189
	v_mov_b32_e32 v94, v189
	v_mov_b32_e32 v95, v189
	v_mov_b32_e32 v96, 0
	v_mov_b32_e32 v97, v189
	v_mov_b32_e32 v98, v189
	v_mov_b32_e32 v99, v189
	v_mov_b32_e32 v100, v189
	v_mov_b32_e32 v101, v189
	v_mov_b32_e32 v102, v189
	v_mov_b32_e32 v103, v189
	v_mov_b32_e32 v104, v189
	v_mov_b32_e32 v105, v189
	v_mov_b32_e32 v106, v189
	v_mov_b32_e32 v107, v189
	v_mov_b32_e32 v108, v189
	v_mov_b32_e32 v109, v189
	v_mov_b32_e32 v110, v189
	v_mov_b32_e32 v111, v189
	v_mov_b32_e32 v112, 0
	v_mov_b32_e32 v113, v189
	v_mov_b32_e32 v114, v189
	v_mov_b32_e32 v115, v189
	v_mov_b32_e32 v116, v189
	v_mov_b32_e32 v117, v189
	v_mov_b32_e32 v118, v189
	v_mov_b32_e32 v119, v189
	v_mov_b32_e32 v120, v189
	v_mov_b32_e32 v121, v189
	v_mov_b32_e32 v122, v189
	v_mov_b32_e32 v123, v189
	v_mov_b32_e32 v124, v189
	v_mov_b32_e32 v125, v189
	v_mov_b32_e32 v126, v189
	v_mov_b32_e32 v127, v189
	.p2align	6

; DI f32x16 fzero() { f32x16 z; for (int i = 0; i < 16; ++i) z[i] = 0.f; return z; }
; template <int NT, class Epi>
; DI void gemm_tile(const u16* __restrict__ A, int lda, const u16* __restrict__ Bt, int ldb, int K, int m0, int n0, const Epi& epi, char* smem) {
;   constexpr int BN = 64 * NT, NB8 = 2 * NT;
;   u16* As = (u16*)smem;
;   u16* Bs = As + 128 * 72;
;   const int tid = threadIdx.x, lane = tid & 63, wave = tid >> 6, r = lane & 31, h = lane >> 5;
;   const int wm = wave >> 1, wn = wave & 1;
;   f32x16 acc[2][NT];
; #pragma unroll
;   for (int a = 0; a < 2; ++a)
; #pragma unroll
;     for (int b = 0; b < NT; ++b) acc[a][b] = fzero();
;   u32x4 ra[4], rb[NB8];
;   const int lrow = tid >> 3, lch = tid & 7;
;   const u16* Ap = A + (size_t)(m0 + lrow) * lda + lch * 8;
;   const u16* Bp = Bt + (size_t)(n0 + lrow) * ldb + lch * 8;
; #pragma unroll
;   for (int i = 0; i < 4; ++i) ra[i] = *(const u32x4*)(Ap + (size_t)(32 * i) * lda);
; #pragma unroll
;   for (int i = 0; i < NB8; ++i) rb[i] = *(const u32x4*)(Bp + (size_t)(32 * i) * ldb);
;     ...
;       for (int q = lb; q < 64 * ntn; q += nlb) {
;         const int tm = x * 64 + q / ntn, tn = q % ntn;
;         gemm_tile<NTM>(A, lda, Bt, ldb, K, tm * 128, tn * (64 * NTM), epi, smem);
.LBB0_675:
	s_bfe_u32 s14, s33, 0x60002
	s_lshl_b32 s15, s14, 7
	v_add_lshl_u32 v182, v197, s15, 11
	s_lshl_b32 s15, s16, 11
	s_or_b32 s14, s14, s3
	s_and_b32 s15, s15, 0x180000
	s_lshl_b32 s36, s14, 7
	v_lshl_add_u64 v[194:195], v[190:191], 0, v[182:183]
	v_or_b32_e32 v182, s15, v199
	s_lshl_b32 s14, s33, 8
	v_or_b32_e32 v0, s36, v186
	v_lshl_add_u64 v[200:201], v[190:191], 0, v[182:183]
	s_and_b32 s37, s14, 0x300
	v_lshlrev_b32_e32 v182, 11, v0
	v_lshl_add_u64 v[0:1], v[184:185], 0, v[182:183]
	v_or_b32_e32 v2, s37, v186
	v_lshlrev_b32_e32 v182, 11, v2
	v_add_co_u32_e32 v2, vcc, s18, v0
	s_mov_b64 s[14:15], 0
	s_nop 0
	v_addc_co_u32_e32 v3, vcc, 0, v1, vcc
	global_load_dwordx4 v[128:131], v[0:1], off
	global_load_dwordx4 v[132:135], v[2:3], off
	v_add_co_u32_e32 v2, vcc, s19, v0
	v_mov_b32_e32 v6, v183
	s_nop 0
	v_addc_co_u32_e32 v3, vcc, 0, v1, vcc
	v_add_co_u32_e32 v0, vcc, s20, v0
	v_mov_b32_e32 v7, v183
	s_nop 0
	v_addc_co_u32_e32 v1, vcc, 0, v1, vcc
	global_load_dwordx4 v[136:139], v[2:3], off
	global_load_dwordx4 v[140:143], v[0:1], off
	v_lshl_add_u64 v[0:1], v[188:189], 0, v[182:183]
	v_add_co_u32_e32 v2, vcc, s18, v0
	v_mov_b32_e32 v8, v183
	s_nop 0
	v_addc_co_u32_e32 v3, vcc, 0, v1, vcc
	global_load_dwordx4 v[144:147], v[0:1], off
	global_load_dwordx4 v[148:151], v[2:3], off
	v_add_co_u32_e32 v2, vcc, s19, v0
	v_mov_b32_e32 v9, v183
	s_nop 0
	v_addc_co_u32_e32 v3, vcc, 0, v1, vcc
	v_add_co_u32_e32 v4, vcc, s20, v0
	v_mov_b32_e32 v10, v183
	s_nop 0
	v_addc_co_u32_e32 v5, vcc, 0, v1, vcc
	global_load_dwordx4 v[152:155], v[2:3], off
	global_load_dwordx4 v[156:159], v[4:5], off
	v_add_co_u32_e32 v2, vcc, s21, v0
	v_mov_b32_e32 v11, v183
	s_nop 0
	v_addc_co_u32_e32 v3, vcc, 0, v1, vcc
	v_add_co_u32_e32 v4, vcc, 0x50000, v0
	v_mov_b32_e32 v12, v183
	s_nop 0
	v_addc_co_u32_e32 v5, vcc, 0, v1, vcc
	global_load_dwordx4 v[160:163], v[2:3], off
	global_load_dwordx4 v[164:167], v[4:5], off
	v_add_co_u32_e32 v2, vcc, 0x60000, v0
	v_mov_b32_e32 v4, v183
	s_nop 0
	v_addc_co_u32_e32 v3, vcc, 0, v1, vcc
	v_add_co_u32_e32 v0, vcc, 0x70000, v0
	v_mov_b32_e32 v5, v183
	s_nop 0
	v_addc_co_u32_e32 v1, vcc, 0, v1, vcc
	global_load_dwordx4 v[168:171], v[2:3], off
	global_load_dwordx4 v[172:175], v[0:1], off
	v_mov_b32_e32 v0, 0
	v_mov_b32_e32 v1, v183
	v_mov_b32_e32 v2, v183
	v_mov_b32_e32 v3, v183
	v_mov_b32_e32 v13, v183
	v_mov_b32_e32 v14, v183
	v_mov_b32_e32 v15, v183
	v_mov_b32_e32 v16, 0
	v_mov_b32_e32 v17, v183
	v_mov_b32_e32 v18, v183
	v_mov_b32_e32 v19, v183
	v_mov_b32_e32 v20, v183
	v_mov_b32_e32 v21, v183
	v_mov_b32_e32 v22, v183
	v_mov_b32_e32 v23, v183
	v_mov_b32_e32 v24, v183
	v_mov_b32_e32 v25, v183
	v_mov_b32_e32 v26, v183
	v_mov_b32_e32 v27, v183
	v_mov_b32_e32 v28, v183
	v_mov_b32_e32 v29, v183
	v_mov_b32_e32 v30, v183
	v_mov_b32_e32 v31, v183
	s_waitcnt vmcnt(13)
	v_mov_b32_e32 v32, 0
	v_mov_b32_e32 v33, v183
	v_mov_b32_e32 v34, v183
	v_mov_b32_e32 v35, v183
	s_waitcnt vmcnt(12)
	v_mov_b32_e32 v36, v183
	v_mov_b32_e32 v37, v183
	v_mov_b32_e32 v38, v183
	v_mov_b32_e32 v39, v183
	v_mov_b32_e32 v40, v183
	v_mov_b32_e32 v41, v183
	v_mov_b32_e32 v42, v183
	v_mov_b32_e32 v43, v183
	v_mov_b32_e32 v44, v183
	v_mov_b32_e32 v45, v183
	v_mov_b32_e32 v46, v183
	v_mov_b32_e32 v47, v183
	v_mov_b32_e32 v48, 0
	v_mov_b32_e32 v49, v183
	v_mov_b32_e32 v50, v183
	v_mov_b32_e32 v51, v183
	v_mov_b32_e32 v52, v183
	v_mov_b32_e32 v53, v183
	v_mov_b32_e32 v54, v183
	v_mov_b32_e32 v55, v183
	v_mov_b32_e32 v56, v183
	v_mov_b32_e32 v57, v183
	v_mov_b32_e32 v58, v183
	v_mov_b32_e32 v59, v183
	v_mov_b32_e32 v60, v183
	v_mov_b32_e32 v61, v183
	v_mov_b32_e32 v62, v183
	v_mov_b32_e32 v63, v183
	v_mov_b32_e32 v64, 0
	v_mov_b32_e32 v65, v183
	v_mov_b32_e32 v66, v183
	v_mov_b32_e32 v67, v183
	v_mov_b32_e32 v68, v183
	v_mov_b32_e32 v69, v183
	v_mov_b32_e32 v70, v183
	v_mov_b32_e32 v71, v183
	v_mov_b32_e32 v72, v183
	v_mov_b32_e32 v73, v183
	v_mov_b32_e32 v74, v183
	v_mov_b32_e32 v75, v183
	v_mov_b32_e32 v76, v183
	v_mov_b32_e32 v77, v183
	v_mov_b32_e32 v78, v183
	v_mov_b32_e32 v79, v183
	v_mov_b32_e32 v80, 0
	v_mov_b32_e32 v81, v183
	v_mov_b32_e32 v82, v183
	v_mov_b32_e32 v83, v183
	v_mov_b32_e32 v84, v183
	v_mov_b32_e32 v85, v183
	v_mov_b32_e32 v86, v183
	v_mov_b32_e32 v87, v183
	v_mov_b32_e32 v88, v183
	v_mov_b32_e32 v89, v183
	v_mov_b32_e32 v90, v183
	v_mov_b32_e32 v91, v183
	v_mov_b32_e32 v92, v183
	v_mov_b32_e32 v93, v183
	v_mov_b32_e32 v94, v183
	v_mov_b32_e32 v95, v183
	v_mov_b32_e32 v96, 0
	v_mov_b32_e32 v97, v183
	v_mov_b32_e32 v98, v183
	v_mov_b32_e32 v99, v183
	v_mov_b32_e32 v100, v183
	v_mov_b32_e32 v101, v183
	v_mov_b32_e32 v102, v183
	v_mov_b32_e32 v103, v183
	v_mov_b32_e32 v104, v183
	v_mov_b32_e32 v105, v183
	v_mov_b32_e32 v106, v183
	v_mov_b32_e32 v107, v183
	v_mov_b32_e32 v108, v183
	v_mov_b32_e32 v109, v183
	v_mov_b32_e32 v110, v183
	v_mov_b32_e32 v111, v183
	v_mov_b32_e32 v112, 0
	v_mov_b32_e32 v113, v183
	v_mov_b32_e32 v114, v183
	v_mov_b32_e32 v115, v183
	v_mov_b32_e32 v116, v183
	v_mov_b32_e32 v117, v183
	v_mov_b32_e32 v118, v183
	v_mov_b32_e32 v119, v183
	v_mov_b32_e32 v120, v183
	v_mov_b32_e32 v121, v183
	v_mov_b32_e32 v122, v183
	v_mov_b32_e32 v123, v183
	v_mov_b32_e32 v124, v183
	v_mov_b32_e32 v125, v183
	v_mov_b32_e32 v126, v183
	v_mov_b32_e32 v127, v183
	.p2align	6
